# GEMM K-loop hand-over trim: s_setprio 1 before the phase barrier, redundant post-barrier lgkmcnt(0) removed, s_setprio 0 after the barrier (P1/P3/P4, 14 sites each)
# speedup vs baseline: 1.0026x; 1.0026x over previous
.LBB0_119:
	s_ashr_i32 s25, s24, 31
	s_lshl_b64 s[26:27], s[24:25], 19
	s_add_u32 s26, s70, s26
	s_addc_u32 s27, s71, s27
	s_and_b64 s[28:29], s[8:9], exec
	s_cselect_b32 s5, s27, s31
	s_cselect_b32 s7, s26, s30
	s_ashr_i32 s23, s22, 31
	s_lshl_b64 s[28:29], s[22:23], 19
	s_add_u32 s28, s2, s28
	s_addc_u32 s29, s3, s29
	s_and_b64 s[36:37], s[8:9], exec
	s_cselect_b32 s23, s29, s35
	s_cselect_b32 s25, s28, s34
	s_add_u32 s30, s30, 0x40080
	s_addc_u32 s31, s31, 0
	s_add_u32 s57, s34, 0x100
	s_addc_u32 s58, s35, 0
	s_mov_b32 s59, -2
	ds_read_b128 v[72:75], v175
	ds_read_b128 v[76:79], v175 offset:1024
	ds_read_b128 v[88:91], v175 offset:2048
	ds_read_b128 v[92:95], v175 offset:3072
	ds_read_b128 v[162:165], v176
	ds_read_b128 v[166:169], v176 offset:1024
	ds_read_b128 v[180:183], v176 offset:2048
	ds_read_b128 v[184:187], v176 offset:3072
	s_add_u32 s34, s30, 0xfffc0080
	s_addc_u32 s35, s31, -1
	s_cmp_eq_u32 s59, 12
	s_cselect_b32 s37, s5, s35
	s_cselect_b32 s36, s7, s34
	s_cselect_b32 s35, s23, s58
	s_cselect_b32 s34, s25, s57
	v_lshl_add_u64 v[170:171], s[30:31], 0, v[154:155]
	s_add_i32 m0, s76, 0xc000
	ds_read_b128 v[188:191], v177
	ds_read_b128 v[192:195], v177 offset:1024
	ds_read_b128 v[198:201], v177 offset:2048
	ds_read_b128 v[202:205], v177 offset:3072
	ds_read_b128 v[206:209], v177 offset:4096
	ds_read_b128 v[210:213], v177 offset:5120
	ds_read_b128 v[214:217], v177 offset:6144
	ds_read_b128 v[218:221], v177 offset:7168
	global_load_lds_dwordx4 v[170:171], off
	v_lshl_add_u64 v[170:171], s[30:31], 0, v[156:157]
	s_add_i32 m0, s76, 0xe000
	s_nop 0
	global_load_lds_dwordx4 v[170:171], off
	s_waitcnt vmcnt(8)
	s_waitcnt lgkmcnt(0)
	s_setprio 1
	s_barrier
	v_mfma_f32_16x16x32_bf16 v[140:143], v[72:75], v[188:191], 0
	v_mfma_f32_16x16x32_bf16 v[136:139], v[88:91], v[188:191], 0
	v_mfma_f32_16x16x32_bf16 v[124:127], v[72:75], v[198:201], 0
	v_mfma_f32_16x16x32_bf16 v[120:123], v[88:91], v[198:201], 0
	v_mfma_f32_16x16x32_bf16 v[108:111], v[72:75], v[206:209], 0
	v_mfma_f32_16x16x32_bf16 v[104:107], v[88:91], v[206:209], 0
	v_mfma_f32_16x16x32_bf16 v[84:87], v[72:75], v[214:217], 0
	v_mfma_f32_16x16x32_bf16 v[80:83], v[88:91], v[214:217], 0
	v_mfma_f32_16x16x32_bf16 v[140:143], v[76:79], v[192:195], v[140:143]
	v_mfma_f32_16x16x32_bf16 v[136:139], v[92:95], v[192:195], v[136:139]
	v_mfma_f32_16x16x32_bf16 v[124:127], v[76:79], v[202:205], v[124:127]
	v_mfma_f32_16x16x32_bf16 v[120:123], v[92:95], v[202:205], v[120:123]
	v_mfma_f32_16x16x32_bf16 v[108:111], v[76:79], v[210:213], v[108:111]
	v_mfma_f32_16x16x32_bf16 v[104:107], v[92:95], v[210:213], v[104:107]
	v_mfma_f32_16x16x32_bf16 v[84:87], v[76:79], v[218:221], v[84:87]
	v_mfma_f32_16x16x32_bf16 v[80:83], v[92:95], v[218:221], v[80:83]
	s_setprio 0
	s_setprio 1
	v_mfma_f32_16x16x32_bf16 v[132:135], v[162:165], v[188:191], 0
	v_mfma_f32_16x16x32_bf16 v[128:131], v[180:183], v[188:191], 0
	v_mfma_f32_16x16x32_bf16 v[116:119], v[162:165], v[198:201], 0
	v_mfma_f32_16x16x32_bf16 v[112:115], v[180:183], v[198:201], 0
	v_mfma_f32_16x16x32_bf16 v[100:103], v[162:165], v[206:209], 0
	v_mfma_f32_16x16x32_bf16 v[96:99], v[180:183], v[206:209], 0
	v_mfma_f32_16x16x32_bf16 v[68:71], v[162:165], v[214:217], 0
	v_mfma_f32_16x16x32_bf16 v[64:67], v[180:183], v[214:217], 0
	v_mfma_f32_16x16x32_bf16 v[132:135], v[166:169], v[192:195], v[132:135]
	v_mfma_f32_16x16x32_bf16 v[128:131], v[184:187], v[192:195], v[128:131]
	v_mfma_f32_16x16x32_bf16 v[116:119], v[166:169], v[202:205], v[116:119]
	v_mfma_f32_16x16x32_bf16 v[112:115], v[184:187], v[202:205], v[112:115]
	v_mfma_f32_16x16x32_bf16 v[100:103], v[166:169], v[210:213], v[100:103]
	v_mfma_f32_16x16x32_bf16 v[96:99], v[184:187], v[210:213], v[96:99]
	v_mfma_f32_16x16x32_bf16 v[68:71], v[166:169], v[218:221], v[68:71]
	v_mfma_f32_16x16x32_bf16 v[64:67], v[184:187], v[218:221], v[64:67]
	s_barrier
	s_setprio 0
	s_add_i32 s60, s50, s33
	v_lshl_add_u64 v[170:171], s[34:35], 0, v[146:147]
	s_mov_b32 m0, s60
	ds_read_b128 v[188:191], v177 offset:16384
	ds_read_b128 v[192:195], v177 offset:17408
	ds_read_b128 v[198:201], v177 offset:18432
	ds_read_b128 v[202:205], v177 offset:19456
	ds_read_b128 v[206:209], v177 offset:20480
	ds_read_b128 v[210:213], v177 offset:21504
	ds_read_b128 v[214:217], v177 offset:22528
	ds_read_b128 v[218:221], v177 offset:23552
	global_load_lds_dwordx4 v[170:171], off
	s_add_i32 m0, s60, 0x2000
	s_add_u32 s60, s34, 0x40000
	v_lshl_add_u64 v[196:197], s[34:35], 0, v[150:151]
	s_addc_u32 s61, s35, 0
	s_add_i32 s62, s51, s33
	global_load_lds_dwordx4 v[196:197], off
	v_lshl_add_u64 v[222:223], s[60:61], 0, v[146:147]
	s_mov_b32 m0, s62
	v_lshl_add_u64 v[224:225], s[36:37], 0, v[148:149]
	global_load_lds_dwordx4 v[222:223], off
	v_lshl_add_u64 v[222:223], s[60:61], 0, v[150:151]
	s_add_i32 m0, s62, 0x2000
	s_nop 0
	global_load_lds_dwordx4 v[222:223], off
	v_lshl_add_u64 v[222:223], s[36:37], 0, v[144:145]
	s_mov_b32 m0, s76
	s_nop 0
	global_load_lds_dwordx4 v[222:223], off
	s_mov_b32 m0, s38
	s_nop 0
	global_load_lds_dwordx4 v[224:225], off
	s_waitcnt vmcnt(8)
	s_waitcnt lgkmcnt(0)
	s_setprio 1
	s_barrier
	v_mfma_f32_16x16x32_bf16 v[60:63], v[72:75], v[188:191], 0
	v_mfma_f32_16x16x32_bf16 v[56:59], v[88:91], v[188:191], 0
	v_mfma_f32_16x16x32_bf16 v[44:47], v[72:75], v[198:201], 0
	v_mfma_f32_16x16x32_bf16 v[40:43], v[88:91], v[198:201], 0
	v_mfma_f32_16x16x32_bf16 v[28:31], v[72:75], v[206:209], 0
	v_mfma_f32_16x16x32_bf16 v[24:27], v[88:91], v[206:209], 0
	v_mfma_f32_16x16x32_bf16 v[12:15], v[72:75], v[214:217], 0
	v_mfma_f32_16x16x32_bf16 v[8:11], v[88:91], v[214:217], 0
	v_mfma_f32_16x16x32_bf16 v[60:63], v[76:79], v[192:195], v[60:63]
	v_mfma_f32_16x16x32_bf16 v[56:59], v[92:95], v[192:195], v[56:59]
	v_mfma_f32_16x16x32_bf16 v[44:47], v[76:79], v[202:205], v[44:47]
	v_mfma_f32_16x16x32_bf16 v[40:43], v[92:95], v[202:205], v[40:43]
	v_mfma_f32_16x16x32_bf16 v[28:31], v[76:79], v[210:213], v[28:31]
	v_mfma_f32_16x16x32_bf16 v[24:27], v[92:95], v[210:213], v[24:27]
	v_mfma_f32_16x16x32_bf16 v[12:15], v[76:79], v[218:221], v[12:15]
	v_mfma_f32_16x16x32_bf16 v[8:11], v[92:95], v[218:221], v[8:11]
	s_setprio 0
	s_setprio 1
	v_mfma_f32_16x16x32_bf16 v[52:55], v[162:165], v[188:191], 0
	v_mfma_f32_16x16x32_bf16 v[48:51], v[180:183], v[188:191], 0
	v_mfma_f32_16x16x32_bf16 v[36:39], v[162:165], v[198:201], 0
	v_mfma_f32_16x16x32_bf16 v[32:35], v[180:183], v[198:201], 0
	v_mfma_f32_16x16x32_bf16 v[20:23], v[162:165], v[206:209], 0
	v_mfma_f32_16x16x32_bf16 v[16:19], v[180:183], v[206:209], 0
	v_mfma_f32_16x16x32_bf16 v[4:7], v[162:165], v[214:217], 0
	v_mfma_f32_16x16x32_bf16 v[0:3], v[180:183], v[214:217], 0
	v_mfma_f32_16x16x32_bf16 v[52:55], v[166:169], v[192:195], v[52:55]
	v_mfma_f32_16x16x32_bf16 v[48:51], v[184:187], v[192:195], v[48:51]
	v_mfma_f32_16x16x32_bf16 v[36:39], v[166:169], v[202:205], v[36:39]
	v_mfma_f32_16x16x32_bf16 v[32:35], v[184:187], v[202:205], v[32:35]
	v_mfma_f32_16x16x32_bf16 v[20:23], v[166:169], v[210:213], v[20:23]
	v_mfma_f32_16x16x32_bf16 v[16:19], v[184:187], v[210:213], v[16:19]
	v_mfma_f32_16x16x32_bf16 v[4:7], v[166:169], v[218:221], v[4:7]
	v_mfma_f32_16x16x32_bf16 v[0:3], v[184:187], v[218:221], v[0:3]
	s_barrier
	s_setprio 0
	s_branch .Lmid_p1
.LBB0_120:
	ds_read_b128 v[72:75], v175
	ds_read_b128 v[76:79], v175 offset:1024
	ds_read_b128 v[88:91], v175 offset:2048
	ds_read_b128 v[92:95], v175 offset:3072
	ds_read_b128 v[162:165], v176
	ds_read_b128 v[166:169], v176 offset:1024
	ds_read_b128 v[180:183], v176 offset:2048
	ds_read_b128 v[184:187], v176 offset:3072
	s_add_u32 s34, s30, 0xfffc0080
	s_addc_u32 s35, s31, -1
	s_cmp_eq_u32 s59, 12
	s_cselect_b32 s37, s5, s35
	s_cselect_b32 s36, s7, s34
	s_cselect_b32 s35, s23, s58
	s_cselect_b32 s34, s25, s57
	v_lshl_add_u64 v[170:171], s[30:31], 0, v[154:155]
	s_add_i32 m0, s76, 0xc000
	ds_read_b128 v[188:191], v177
	ds_read_b128 v[192:195], v177 offset:1024
	ds_read_b128 v[198:201], v177 offset:2048
	ds_read_b128 v[202:205], v177 offset:3072
	ds_read_b128 v[206:209], v177 offset:4096
	ds_read_b128 v[210:213], v177 offset:5120
	ds_read_b128 v[214:217], v177 offset:6144
	ds_read_b128 v[218:221], v177 offset:7168
	global_load_lds_dwordx4 v[170:171], off
	v_lshl_add_u64 v[170:171], s[30:31], 0, v[156:157]
	s_add_i32 m0, s76, 0xe000
	s_nop 0
	global_load_lds_dwordx4 v[170:171], off
	s_waitcnt vmcnt(8)
	s_waitcnt lgkmcnt(0)
	s_setprio 1
	s_barrier
	v_mfma_f32_16x16x32_bf16 v[140:143], v[72:75], v[188:191], v[140:143]
	v_mfma_f32_16x16x32_bf16 v[136:139], v[88:91], v[188:191], v[136:139]
	v_mfma_f32_16x16x32_bf16 v[124:127], v[72:75], v[198:201], v[124:127]
	v_mfma_f32_16x16x32_bf16 v[120:123], v[88:91], v[198:201], v[120:123]
	v_mfma_f32_16x16x32_bf16 v[108:111], v[72:75], v[206:209], v[108:111]
	v_mfma_f32_16x16x32_bf16 v[104:107], v[88:91], v[206:209], v[104:107]
	v_mfma_f32_16x16x32_bf16 v[84:87], v[72:75], v[214:217], v[84:87]
	v_mfma_f32_16x16x32_bf16 v[80:83], v[88:91], v[214:217], v[80:83]
	v_mfma_f32_16x16x32_bf16 v[140:143], v[76:79], v[192:195], v[140:143]
	v_mfma_f32_16x16x32_bf16 v[136:139], v[92:95], v[192:195], v[136:139]
	v_mfma_f32_16x16x32_bf16 v[124:127], v[76:79], v[202:205], v[124:127]
	v_mfma_f32_16x16x32_bf16 v[120:123], v[92:95], v[202:205], v[120:123]
	v_mfma_f32_16x16x32_bf16 v[108:111], v[76:79], v[210:213], v[108:111]
	v_mfma_f32_16x16x32_bf16 v[104:107], v[92:95], v[210:213], v[104:107]
	v_mfma_f32_16x16x32_bf16 v[84:87], v[76:79], v[218:221], v[84:87]
	v_mfma_f32_16x16x32_bf16 v[80:83], v[92:95], v[218:221], v[80:83]
	s_setprio 0
	s_setprio 1
	v_mfma_f32_16x16x32_bf16 v[132:135], v[162:165], v[188:191], v[132:135]
	v_mfma_f32_16x16x32_bf16 v[128:131], v[180:183], v[188:191], v[128:131]
	v_mfma_f32_16x16x32_bf16 v[116:119], v[162:165], v[198:201], v[116:119]
	v_mfma_f32_16x16x32_bf16 v[112:115], v[180:183], v[198:201], v[112:115]
	v_mfma_f32_16x16x32_bf16 v[100:103], v[162:165], v[206:209], v[100:103]
	v_mfma_f32_16x16x32_bf16 v[96:99], v[180:183], v[206:209], v[96:99]
	v_mfma_f32_16x16x32_bf16 v[68:71], v[162:165], v[214:217], v[68:71]
	v_mfma_f32_16x16x32_bf16 v[64:67], v[180:183], v[214:217], v[64:67]
	v_mfma_f32_16x16x32_bf16 v[132:135], v[166:169], v[192:195], v[132:135]
	v_mfma_f32_16x16x32_bf16 v[128:131], v[184:187], v[192:195], v[128:131]
	v_mfma_f32_16x16x32_bf16 v[116:119], v[166:169], v[202:205], v[116:119]
	v_mfma_f32_16x16x32_bf16 v[112:115], v[184:187], v[202:205], v[112:115]
	v_mfma_f32_16x16x32_bf16 v[100:103], v[166:169], v[210:213], v[100:103]
	v_mfma_f32_16x16x32_bf16 v[96:99], v[184:187], v[210:213], v[96:99]
	v_mfma_f32_16x16x32_bf16 v[68:71], v[166:169], v[218:221], v[68:71]
	v_mfma_f32_16x16x32_bf16 v[64:67], v[184:187], v[218:221], v[64:67]
	s_barrier
	s_setprio 0
	s_add_i32 s60, s50, s33
	v_lshl_add_u64 v[170:171], s[34:35], 0, v[146:147]
	s_mov_b32 m0, s60
	ds_read_b128 v[188:191], v177 offset:16384
	ds_read_b128 v[192:195], v177 offset:17408
	ds_read_b128 v[198:201], v177 offset:18432
	ds_read_b128 v[202:205], v177 offset:19456
	ds_read_b128 v[206:209], v177 offset:20480
	ds_read_b128 v[210:213], v177 offset:21504
	ds_read_b128 v[214:217], v177 offset:22528
	ds_read_b128 v[218:221], v177 offset:23552
	global_load_lds_dwordx4 v[170:171], off
	s_add_i32 m0, s60, 0x2000
	s_add_u32 s60, s34, 0x40000
	v_lshl_add_u64 v[196:197], s[34:35], 0, v[150:151]
	s_addc_u32 s61, s35, 0
	s_add_i32 s62, s51, s33
	global_load_lds_dwordx4 v[196:197], off
	v_lshl_add_u64 v[222:223], s[60:61], 0, v[146:147]
	s_mov_b32 m0, s62
	v_lshl_add_u64 v[224:225], s[36:37], 0, v[148:149]
	global_load_lds_dwordx4 v[222:223], off
	v_lshl_add_u64 v[222:223], s[60:61], 0, v[150:151]
	s_add_i32 m0, s62, 0x2000
	s_nop 0
	global_load_lds_dwordx4 v[222:223], off
	v_lshl_add_u64 v[222:223], s[36:37], 0, v[144:145]
	s_mov_b32 m0, s76
	s_nop 0
	global_load_lds_dwordx4 v[222:223], off
	s_mov_b32 m0, s38
	s_nop 0
	global_load_lds_dwordx4 v[224:225], off
	s_waitcnt vmcnt(8)
	s_waitcnt lgkmcnt(0)
	s_setprio 1
	s_barrier
	v_mfma_f32_16x16x32_bf16 v[60:63], v[72:75], v[188:191], v[60:63]
	v_mfma_f32_16x16x32_bf16 v[56:59], v[88:91], v[188:191], v[56:59]
	v_mfma_f32_16x16x32_bf16 v[44:47], v[72:75], v[198:201], v[44:47]
	v_mfma_f32_16x16x32_bf16 v[40:43], v[88:91], v[198:201], v[40:43]
	v_mfma_f32_16x16x32_bf16 v[28:31], v[72:75], v[206:209], v[28:31]
	v_mfma_f32_16x16x32_bf16 v[24:27], v[88:91], v[206:209], v[24:27]
	v_mfma_f32_16x16x32_bf16 v[12:15], v[72:75], v[214:217], v[12:15]
	v_mfma_f32_16x16x32_bf16 v[8:11], v[88:91], v[214:217], v[8:11]
	v_mfma_f32_16x16x32_bf16 v[60:63], v[76:79], v[192:195], v[60:63]
	v_mfma_f32_16x16x32_bf16 v[56:59], v[92:95], v[192:195], v[56:59]
	v_mfma_f32_16x16x32_bf16 v[44:47], v[76:79], v[202:205], v[44:47]
	v_mfma_f32_16x16x32_bf16 v[40:43], v[92:95], v[202:205], v[40:43]
	v_mfma_f32_16x16x32_bf16 v[28:31], v[76:79], v[210:213], v[28:31]
	v_mfma_f32_16x16x32_bf16 v[24:27], v[92:95], v[210:213], v[24:27]
	v_mfma_f32_16x16x32_bf16 v[12:15], v[76:79], v[218:221], v[12:15]
	v_mfma_f32_16x16x32_bf16 v[8:11], v[92:95], v[218:221], v[8:11]
	s_setprio 0
	s_setprio 1
	v_mfma_f32_16x16x32_bf16 v[52:55], v[162:165], v[188:191], v[52:55]
	v_mfma_f32_16x16x32_bf16 v[48:51], v[180:183], v[188:191], v[48:51]
	v_mfma_f32_16x16x32_bf16 v[36:39], v[162:165], v[198:201], v[36:39]
	v_mfma_f32_16x16x32_bf16 v[32:35], v[180:183], v[198:201], v[32:35]
	v_mfma_f32_16x16x32_bf16 v[20:23], v[162:165], v[206:209], v[20:23]
	v_mfma_f32_16x16x32_bf16 v[16:19], v[180:183], v[206:209], v[16:19]
	v_mfma_f32_16x16x32_bf16 v[4:7], v[162:165], v[214:217], v[4:7]
	v_mfma_f32_16x16x32_bf16 v[0:3], v[180:183], v[214:217], v[0:3]
	v_mfma_f32_16x16x32_bf16 v[52:55], v[166:169], v[192:195], v[52:55]
	v_mfma_f32_16x16x32_bf16 v[48:51], v[184:187], v[192:195], v[48:51]
	v_mfma_f32_16x16x32_bf16 v[36:39], v[166:169], v[202:205], v[36:39]
	v_mfma_f32_16x16x32_bf16 v[32:35], v[184:187], v[202:205], v[32:35]
	v_mfma_f32_16x16x32_bf16 v[20:23], v[166:169], v[210:213], v[20:23]
	v_mfma_f32_16x16x32_bf16 v[16:19], v[184:187], v[210:213], v[16:19]
	v_mfma_f32_16x16x32_bf16 v[4:7], v[166:169], v[218:221], v[4:7]
	v_mfma_f32_16x16x32_bf16 v[0:3], v[184:187], v[218:221], v[0:3]
	s_barrier
	s_setprio 0
.Lmid_p1:
	s_add_i32 s60, 0, 0x18000
	s_add_i32 s61, 0, 0x1c000
	v_add_u32_e32 v92, s60, v173
	v_add_u32_e32 v152, s61, v173
	ds_read_b128 v[72:75], v92
	ds_read_b128 v[76:79], v92 offset:1024
	ds_read_b128 v[88:91], v92 offset:2048
	ds_read_b128 v[92:95], v92 offset:3072
	ds_read_b128 v[162:165], v152
	ds_read_b128 v[166:169], v152 offset:1024
	ds_read_b128 v[180:183], v152 offset:2048
	ds_read_b128 v[184:187], v152 offset:3072
	s_add_u32 s36, s36, 0x40000
	s_addc_u32 s37, s37, 0
	s_mov_b32 m0, s39
	v_lshl_add_u64 v[226:227], s[36:37], 0, v[144:145]
	ds_read_b128 v[188:191], v177 offset:32768
	ds_read_b128 v[192:195], v177 offset:33792
	ds_read_b128 v[198:201], v177 offset:34816
	ds_read_b128 v[202:205], v177 offset:35840
	ds_read_b128 v[206:209], v177 offset:36864
	ds_read_b128 v[210:213], v177 offset:37888
	ds_read_b128 v[214:217], v177 offset:38912
	ds_read_b128 v[218:221], v177 offset:39936
	global_load_lds_dwordx4 v[226:227], off
	v_lshl_add_u64 v[226:227], s[36:37], 0, v[148:149]
	s_mov_b32 m0, s40
	s_nop 0
	global_load_lds_dwordx4 v[226:227], off
	s_waitcnt vmcnt(8)
	s_waitcnt lgkmcnt(0)
	s_setprio 1
	s_barrier
	v_mfma_f32_16x16x32_bf16 v[140:143], v[72:75], v[188:191], v[140:143]
	v_mfma_f32_16x16x32_bf16 v[136:139], v[88:91], v[188:191], v[136:139]
	v_mfma_f32_16x16x32_bf16 v[124:127], v[72:75], v[198:201], v[124:127]
	v_mfma_f32_16x16x32_bf16 v[120:123], v[88:91], v[198:201], v[120:123]
	v_mfma_f32_16x16x32_bf16 v[108:111], v[72:75], v[206:209], v[108:111]
	v_mfma_f32_16x16x32_bf16 v[104:107], v[88:91], v[206:209], v[104:107]
	v_mfma_f32_16x16x32_bf16 v[84:87], v[72:75], v[214:217], v[84:87]
	v_mfma_f32_16x16x32_bf16 v[80:83], v[88:91], v[214:217], v[80:83]
	v_mfma_f32_16x16x32_bf16 v[140:143], v[76:79], v[192:195], v[140:143]
	v_mfma_f32_16x16x32_bf16 v[136:139], v[92:95], v[192:195], v[136:139]
	v_mfma_f32_16x16x32_bf16 v[124:127], v[76:79], v[202:205], v[124:127]
	v_mfma_f32_16x16x32_bf16 v[120:123], v[92:95], v[202:205], v[120:123]
	v_mfma_f32_16x16x32_bf16 v[108:111], v[76:79], v[210:213], v[108:111]
	v_mfma_f32_16x16x32_bf16 v[104:107], v[92:95], v[210:213], v[104:107]
	v_mfma_f32_16x16x32_bf16 v[84:87], v[76:79], v[218:221], v[84:87]
	v_mfma_f32_16x16x32_bf16 v[80:83], v[92:95], v[218:221], v[80:83]
	s_setprio 0
	s_setprio 1
	v_mfma_f32_16x16x32_bf16 v[132:135], v[162:165], v[188:191], v[132:135]
	v_mfma_f32_16x16x32_bf16 v[128:131], v[180:183], v[188:191], v[128:131]
	v_mfma_f32_16x16x32_bf16 v[116:119], v[162:165], v[198:201], v[116:119]
	v_mfma_f32_16x16x32_bf16 v[112:115], v[180:183], v[198:201], v[112:115]
	v_mfma_f32_16x16x32_bf16 v[100:103], v[162:165], v[206:209], v[100:103]
	v_mfma_f32_16x16x32_bf16 v[96:99], v[180:183], v[206:209], v[96:99]
	v_mfma_f32_16x16x32_bf16 v[68:71], v[162:165], v[214:217], v[68:71]
	v_mfma_f32_16x16x32_bf16 v[64:67], v[180:183], v[214:217], v[64:67]
	v_mfma_f32_16x16x32_bf16 v[132:135], v[166:169], v[192:195], v[132:135]
	v_mfma_f32_16x16x32_bf16 v[128:131], v[184:187], v[192:195], v[128:131]
	v_mfma_f32_16x16x32_bf16 v[116:119], v[166:169], v[202:205], v[116:119]
	v_mfma_f32_16x16x32_bf16 v[112:115], v[184:187], v[202:205], v[112:115]
	v_mfma_f32_16x16x32_bf16 v[100:103], v[166:169], v[210:213], v[100:103]
	v_mfma_f32_16x16x32_bf16 v[96:99], v[184:187], v[210:213], v[96:99]
	v_mfma_f32_16x16x32_bf16 v[68:71], v[166:169], v[218:221], v[68:71]
	v_mfma_f32_16x16x32_bf16 v[64:67], v[184:187], v[218:221], v[64:67]
	s_barrier
	s_setprio 0
	s_add_i32 s36, s60, s33
	v_lshl_add_u64 v[170:171], v[170:171], 0, s[18:19]
	s_mov_b32 m0, s36
	ds_read_b128 v[188:191], v177 offset:49152
	ds_read_b128 v[192:195], v177 offset:50176
	ds_read_b128 v[198:201], v177 offset:51200
	ds_read_b128 v[202:205], v177 offset:52224
	ds_read_b128 v[206:209], v177 offset:53248
	ds_read_b128 v[210:213], v177 offset:54272
	ds_read_b128 v[214:217], v177 offset:55296
	ds_read_b128 v[218:221], v177 offset:56320
	global_load_lds_dwordx4 v[170:171], off
	s_add_i32 m0, s36, 0x2000
	s_add_u32 s34, s34, 0x40080
	v_lshl_add_u64 v[170:171], v[196:197], 0, s[18:19]
	s_addc_u32 s35, s35, 0
	s_add_i32 s36, s61, s33
	global_load_lds_dwordx4 v[170:171], off
	v_lshl_add_u64 v[170:171], s[34:35], 0, v[146:147]
	s_mov_b32 m0, s36
	s_nop 0
	global_load_lds_dwordx4 v[170:171], off
	v_lshl_add_u64 v[170:171], s[34:35], 0, v[150:151]
	s_add_i32 m0, s36, 0x2000
	s_nop 0
	global_load_lds_dwordx4 v[170:171], off
	v_lshl_add_u64 v[170:171], v[222:223], 0, s[18:19]
	s_mov_b32 m0, s42
	s_nop 0
	global_load_lds_dwordx4 v[170:171], off
	v_lshl_add_u64 v[170:171], v[224:225], 0, s[18:19]
	s_mov_b32 m0, s43
	s_nop 0
	global_load_lds_dwordx4 v[170:171], off
	s_waitcnt vmcnt(8)
	s_waitcnt lgkmcnt(0)
	s_setprio 1
	s_barrier
	v_mfma_f32_16x16x32_bf16 v[60:63], v[72:75], v[188:191], v[60:63]
	v_mfma_f32_16x16x32_bf16 v[56:59], v[88:91], v[188:191], v[56:59]
	v_mfma_f32_16x16x32_bf16 v[44:47], v[72:75], v[198:201], v[44:47]
	v_mfma_f32_16x16x32_bf16 v[40:43], v[88:91], v[198:201], v[40:43]
	v_mfma_f32_16x16x32_bf16 v[28:31], v[72:75], v[206:209], v[28:31]
	v_mfma_f32_16x16x32_bf16 v[24:27], v[88:91], v[206:209], v[24:27]
	v_mfma_f32_16x16x32_bf16 v[12:15], v[72:75], v[214:217], v[12:15]
	v_mfma_f32_16x16x32_bf16 v[8:11], v[88:91], v[214:217], v[8:11]
	v_mfma_f32_16x16x32_bf16 v[60:63], v[76:79], v[192:195], v[60:63]
	v_mfma_f32_16x16x32_bf16 v[56:59], v[92:95], v[192:195], v[56:59]
	v_mfma_f32_16x16x32_bf16 v[44:47], v[76:79], v[202:205], v[44:47]
	v_mfma_f32_16x16x32_bf16 v[40:43], v[92:95], v[202:205], v[40:43]
	v_mfma_f32_16x16x32_bf16 v[28:31], v[76:79], v[210:213], v[28:31]
	v_mfma_f32_16x16x32_bf16 v[24:27], v[92:95], v[210:213], v[24:27]
	v_mfma_f32_16x16x32_bf16 v[12:15], v[76:79], v[218:221], v[12:15]
	v_mfma_f32_16x16x32_bf16 v[8:11], v[92:95], v[218:221], v[8:11]
	s_setprio 0
	s_setprio 1
	v_mfma_f32_16x16x32_bf16 v[52:55], v[162:165], v[188:191], v[52:55]
	v_mfma_f32_16x16x32_bf16 v[48:51], v[180:183], v[188:191], v[48:51]
	v_mfma_f32_16x16x32_bf16 v[36:39], v[162:165], v[198:201], v[36:39]
	v_mfma_f32_16x16x32_bf16 v[32:35], v[180:183], v[198:201], v[32:35]
	v_mfma_f32_16x16x32_bf16 v[20:23], v[162:165], v[206:209], v[20:23]
	v_mfma_f32_16x16x32_bf16 v[16:19], v[180:183], v[206:209], v[16:19]
	v_mfma_f32_16x16x32_bf16 v[4:7], v[162:165], v[214:217], v[4:7]
	v_mfma_f32_16x16x32_bf16 v[0:3], v[180:183], v[214:217], v[0:3]
	v_mfma_f32_16x16x32_bf16 v[52:55], v[166:169], v[192:195], v[52:55]
	v_mfma_f32_16x16x32_bf16 v[48:51], v[184:187], v[192:195], v[48:51]
	v_mfma_f32_16x16x32_bf16 v[36:39], v[166:169], v[202:205], v[36:39]
	v_mfma_f32_16x16x32_bf16 v[32:35], v[184:187], v[202:205], v[32:35]
	v_mfma_f32_16x16x32_bf16 v[20:23], v[166:169], v[210:213], v[20:23]
	v_mfma_f32_16x16x32_bf16 v[16:19], v[184:187], v[210:213], v[16:19]
	v_mfma_f32_16x16x32_bf16 v[4:7], v[166:169], v[218:221], v[4:7]
	v_mfma_f32_16x16x32_bf16 v[0:3], v[184:187], v[218:221], v[0:3]
	s_barrier
	s_setprio 0
	s_add_i32 s59, s59, 2
	s_add_u32 s30, s30, 0x100
	s_addc_u32 s31, s31, 0
	s_add_u32 s57, s57, 0x100
	s_addc_u32 s58, s58, 0
	s_cmp_gt_u32 s59, 13
	s_cbranch_scc0 .LBB0_120
	s_and_b64 vcc, exec, s[20:21]
	s_cbranch_vccz .LBB0_123
	s_barrier

.LBB0_535:
	s_add_u32 s26, s22, s24
	s_addc_u32 s27, s23, s25
	s_add_u32 s26, s26, 0x100
	s_addc_u32 s27, s27, 0
	s_add_u32 s53, s50, s24
	s_addc_u32 s54, s51, s25
	s_add_i32 s55, 0, 0x10000
	v_add_u32_e32 v1, s55, v223
	ds_read_b128 v[132:135], v1
	ds_read_b128 v[136:139], v1 offset:1024
	ds_read_b128 v[140:143], v1 offset:2048
	ds_read_b128 v[144:147], v1 offset:3072
	v_add_u32_e32 v1, s45, v223
	ds_read_b128 v[148:151], v1
	ds_read_b128 v[152:155], v1 offset:1024
	ds_read_b128 v[156:159], v1 offset:2048
	ds_read_b128 v[160:163], v1 offset:3072
	s_cmpk_eq_i32 s24, 0x700
	s_cselect_b32 s29, s17, s27
	s_cselect_b32 s28, s46, s26
	s_cselect_b32 s27, s48, s54
	s_cselect_b32 s26, s49, s53
	v_lshl_add_u64 v[2:3], v[214:215], 0, s[24:25]
	s_add_i32 m0, s76, 0xc000
	ds_read_b128 v[164:167], v224
	ds_read_b128 v[168:171], v224 offset:1024
	ds_read_b128 v[172:175], v224 offset:2048
	ds_read_b128 v[176:179], v224 offset:3072
	ds_read_b128 v[180:183], v224 offset:4096
	ds_read_b128 v[184:187], v224 offset:5120
	ds_read_b128 v[188:191], v224 offset:6144
	ds_read_b128 v[192:195], v224 offset:7168
	global_load_lds_dwordx4 v[2:3], off
	v_lshl_add_u64 v[2:3], v[216:217], 0, s[24:25]
	s_add_i32 m0, s76, 0xe000
	s_nop 0
	global_load_lds_dwordx4 v[2:3], off
	s_waitcnt vmcnt(8)
	s_waitcnt lgkmcnt(0)
	s_setprio 1
	s_barrier
	v_mfma_f32_16x16x32_bf16 v[128:131], v[132:135], v[164:167], v[128:131]
	v_mfma_f32_16x16x32_bf16 v[124:127], v[140:143], v[164:167], v[124:127]
	v_mfma_f32_16x16x32_bf16 v[112:115], v[132:135], v[172:175], v[112:115]
	v_mfma_f32_16x16x32_bf16 v[108:111], v[140:143], v[172:175], v[108:111]
	v_mfma_f32_16x16x32_bf16 v[96:99], v[132:135], v[180:183], v[96:99]
	v_mfma_f32_16x16x32_bf16 v[92:95], v[140:143], v[180:183], v[92:95]
	v_mfma_f32_16x16x32_bf16 v[80:83], v[132:135], v[188:191], v[80:83]
	v_mfma_f32_16x16x32_bf16 v[76:79], v[140:143], v[188:191], v[76:79]
	v_mfma_f32_16x16x32_bf16 v[128:131], v[136:139], v[168:171], v[128:131]
	v_mfma_f32_16x16x32_bf16 v[124:127], v[144:147], v[168:171], v[124:127]
	v_mfma_f32_16x16x32_bf16 v[112:115], v[136:139], v[176:179], v[112:115]
	v_mfma_f32_16x16x32_bf16 v[108:111], v[144:147], v[176:179], v[108:111]
	v_mfma_f32_16x16x32_bf16 v[96:99], v[136:139], v[184:187], v[96:99]
	v_mfma_f32_16x16x32_bf16 v[92:95], v[144:147], v[184:187], v[92:95]
	v_mfma_f32_16x16x32_bf16 v[80:83], v[136:139], v[192:195], v[80:83]
	v_mfma_f32_16x16x32_bf16 v[76:79], v[144:147], v[192:195], v[76:79]
	s_setprio 0
	s_setprio 1
	v_mfma_f32_16x16x32_bf16 v[120:123], v[148:151], v[164:167], v[120:123]
	v_mfma_f32_16x16x32_bf16 v[116:119], v[156:159], v[164:167], v[116:119]
	v_mfma_f32_16x16x32_bf16 v[104:107], v[148:151], v[172:175], v[104:107]
	v_mfma_f32_16x16x32_bf16 v[100:103], v[156:159], v[172:175], v[100:103]
	v_mfma_f32_16x16x32_bf16 v[88:91], v[148:151], v[180:183], v[88:91]
	v_mfma_f32_16x16x32_bf16 v[84:87], v[156:159], v[180:183], v[84:87]
	v_mfma_f32_16x16x32_bf16 v[72:75], v[148:151], v[188:191], v[72:75]
	v_mfma_f32_16x16x32_bf16 v[68:71], v[156:159], v[188:191], v[68:71]
	v_mfma_f32_16x16x32_bf16 v[120:123], v[152:155], v[168:171], v[120:123]
	v_mfma_f32_16x16x32_bf16 v[116:119], v[160:163], v[168:171], v[116:119]
	v_mfma_f32_16x16x32_bf16 v[104:107], v[152:155], v[176:179], v[104:107]
	v_mfma_f32_16x16x32_bf16 v[100:103], v[160:163], v[176:179], v[100:103]
	v_mfma_f32_16x16x32_bf16 v[88:91], v[152:155], v[184:187], v[88:91]
	v_mfma_f32_16x16x32_bf16 v[84:87], v[160:163], v[184:187], v[84:87]
	v_mfma_f32_16x16x32_bf16 v[72:75], v[152:155], v[192:195], v[72:75]
	v_mfma_f32_16x16x32_bf16 v[68:71], v[160:163], v[192:195], v[68:71]
	s_barrier
	s_setprio 0
	s_add_i32 s53, s55, s33
	v_lshl_add_u64 v[218:219], s[26:27], 0, v[200:201]
	s_mov_b32 m0, s53
	ds_read_b128 v[164:167], v224 offset:16384
	ds_read_b128 v[168:171], v224 offset:17408
	ds_read_b128 v[172:175], v224 offset:18432
	ds_read_b128 v[176:179], v224 offset:19456
	ds_read_b128 v[180:183], v224 offset:20480
	ds_read_b128 v[184:187], v224 offset:21504
	ds_read_b128 v[188:191], v224 offset:22528
	ds_read_b128 v[192:195], v224 offset:23552
	global_load_lds_dwordx4 v[218:219], off
	s_add_i32 m0, s53, 0x2000
	s_add_u32 s54, s26, 0x40000
	v_lshl_add_u64 v[220:221], s[26:27], 0, v[204:205]
	s_addc_u32 s55, s27, 0
	s_add_i32 s53, s45, s33
	global_load_lds_dwordx4 v[220:221], off
	v_lshl_add_u64 v[2:3], s[54:55], 0, v[200:201]
	s_mov_b32 m0, s53
	v_lshl_add_u64 v[226:227], s[28:29], 0, v[198:199]
	global_load_lds_dwordx4 v[2:3], off
	v_lshl_add_u64 v[2:3], s[54:55], 0, v[204:205]
	s_add_i32 m0, s53, 0x2000
	v_lshl_add_u64 v[228:229], s[28:29], 0, v[202:203]
	global_load_lds_dwordx4 v[2:3], off
	s_mov_b32 m0, s76
	s_nop 0
	global_load_lds_dwordx4 v[226:227], off
	s_mov_b32 m0, s31
	s_nop 0
	global_load_lds_dwordx4 v[228:229], off
	s_waitcnt vmcnt(8)
	s_waitcnt lgkmcnt(0)
	s_setprio 1
	s_barrier
	v_mfma_f32_16x16x32_bf16 v[64:67], v[132:135], v[164:167], v[64:67]
	v_mfma_f32_16x16x32_bf16 v[60:63], v[140:143], v[164:167], v[60:63]
	v_mfma_f32_16x16x32_bf16 v[48:51], v[132:135], v[172:175], v[48:51]
	v_mfma_f32_16x16x32_bf16 v[44:47], v[140:143], v[172:175], v[44:47]
	v_mfma_f32_16x16x32_bf16 v[32:35], v[132:135], v[180:183], v[32:35]
	v_mfma_f32_16x16x32_bf16 v[28:31], v[140:143], v[180:183], v[28:31]
	v_mfma_f32_16x16x32_bf16 v[16:19], v[132:135], v[188:191], v[16:19]
	v_mfma_f32_16x16x32_bf16 v[12:15], v[140:143], v[188:191], v[12:15]
	v_mfma_f32_16x16x32_bf16 v[64:67], v[136:139], v[168:171], v[64:67]
	v_mfma_f32_16x16x32_bf16 v[60:63], v[144:147], v[168:171], v[60:63]
	v_mfma_f32_16x16x32_bf16 v[48:51], v[136:139], v[176:179], v[48:51]
	v_mfma_f32_16x16x32_bf16 v[44:47], v[144:147], v[176:179], v[44:47]
	v_mfma_f32_16x16x32_bf16 v[32:35], v[136:139], v[184:187], v[32:35]
	v_mfma_f32_16x16x32_bf16 v[28:31], v[144:147], v[184:187], v[28:31]
	v_mfma_f32_16x16x32_bf16 v[16:19], v[136:139], v[192:195], v[16:19]
	v_mfma_f32_16x16x32_bf16 v[12:15], v[144:147], v[192:195], v[12:15]
	s_setprio 0
	s_setprio 1
	v_mfma_f32_16x16x32_bf16 v[56:59], v[148:151], v[164:167], v[56:59]
	v_mfma_f32_16x16x32_bf16 v[52:55], v[156:159], v[164:167], v[52:55]
	v_mfma_f32_16x16x32_bf16 v[40:43], v[148:151], v[172:175], v[40:43]
	v_mfma_f32_16x16x32_bf16 v[36:39], v[156:159], v[172:175], v[36:39]
	v_mfma_f32_16x16x32_bf16 v[24:27], v[148:151], v[180:183], v[24:27]
	v_mfma_f32_16x16x32_bf16 v[20:23], v[156:159], v[180:183], v[20:23]
	v_mfma_f32_16x16x32_bf16 v[8:11], v[148:151], v[188:191], v[8:11]
	v_mfma_f32_16x16x32_bf16 v[2:5], v[156:159], v[188:191], v[4:7]
	v_mfma_f32_16x16x32_bf16 v[56:59], v[152:155], v[168:171], v[56:59]
	v_mfma_f32_16x16x32_bf16 v[52:55], v[160:163], v[168:171], v[52:55]
	v_mfma_f32_16x16x32_bf16 v[40:43], v[152:155], v[176:179], v[40:43]
	v_mfma_f32_16x16x32_bf16 v[36:39], v[160:163], v[176:179], v[36:39]
	v_mfma_f32_16x16x32_bf16 v[24:27], v[152:155], v[184:187], v[24:27]
	v_mfma_f32_16x16x32_bf16 v[20:23], v[160:163], v[184:187], v[20:23]
	v_mfma_f32_16x16x32_bf16 v[8:11], v[152:155], v[192:195], v[8:11]
	v_mfma_f32_16x16x32_bf16 v[2:5], v[160:163], v[192:195], v[2:5]
	s_barrier
	s_setprio 0
	s_add_i32 s53, 0, 0x18000
	v_add_u32_e32 v1, s53, v223
	s_add_i32 s54, 0, 0x1c000
	ds_read_b128 v[132:135], v1
	ds_read_b128 v[136:139], v1 offset:1024
	ds_read_b128 v[140:143], v1 offset:2048
	ds_read_b128 v[144:147], v1 offset:3072
	v_add_u32_e32 v1, s54, v223
	ds_read_b128 v[148:151], v1
	ds_read_b128 v[152:155], v1 offset:1024
	ds_read_b128 v[156:159], v1 offset:2048
	ds_read_b128 v[160:163], v1 offset:3072
	s_add_u32 s28, s28, 0x40000
	s_addc_u32 s29, s29, 0
	s_mov_b32 m0, s34
	v_lshl_add_u64 v[6:7], s[28:29], 0, v[198:199]
	ds_read_b128 v[164:167], v224 offset:32768
	ds_read_b128 v[168:171], v224 offset:33792
	ds_read_b128 v[172:175], v224 offset:34816
	ds_read_b128 v[176:179], v224 offset:35840
	ds_read_b128 v[180:183], v224 offset:36864
	ds_read_b128 v[184:187], v224 offset:37888
	ds_read_b128 v[188:191], v224 offset:38912
	ds_read_b128 v[192:195], v224 offset:39936
	global_load_lds_dwordx4 v[6:7], off
	v_lshl_add_u64 v[6:7], s[28:29], 0, v[202:203]
	s_mov_b32 m0, s35
	s_nop 0
	global_load_lds_dwordx4 v[6:7], off
	s_waitcnt vmcnt(8)
	s_waitcnt lgkmcnt(0)
	s_setprio 1
	s_barrier
	v_mfma_f32_16x16x32_bf16 v[128:131], v[132:135], v[164:167], v[128:131]
	v_mfma_f32_16x16x32_bf16 v[124:127], v[140:143], v[164:167], v[124:127]
	v_mfma_f32_16x16x32_bf16 v[112:115], v[132:135], v[172:175], v[112:115]
	v_mfma_f32_16x16x32_bf16 v[108:111], v[140:143], v[172:175], v[108:111]
	v_mfma_f32_16x16x32_bf16 v[96:99], v[132:135], v[180:183], v[96:99]
	v_mfma_f32_16x16x32_bf16 v[92:95], v[140:143], v[180:183], v[92:95]
	v_mfma_f32_16x16x32_bf16 v[80:83], v[132:135], v[188:191], v[80:83]
	v_mfma_f32_16x16x32_bf16 v[76:79], v[140:143], v[188:191], v[76:79]
	v_mfma_f32_16x16x32_bf16 v[128:131], v[136:139], v[168:171], v[128:131]
	v_mfma_f32_16x16x32_bf16 v[124:127], v[144:147], v[168:171], v[124:127]
	v_mfma_f32_16x16x32_bf16 v[112:115], v[136:139], v[176:179], v[112:115]
	v_mfma_f32_16x16x32_bf16 v[108:111], v[144:147], v[176:179], v[108:111]
	v_mfma_f32_16x16x32_bf16 v[96:99], v[136:139], v[184:187], v[96:99]
	v_mfma_f32_16x16x32_bf16 v[92:95], v[144:147], v[184:187], v[92:95]
	v_mfma_f32_16x16x32_bf16 v[80:83], v[136:139], v[192:195], v[80:83]
	v_mfma_f32_16x16x32_bf16 v[76:79], v[144:147], v[192:195], v[76:79]
	s_setprio 0
	s_setprio 1
	v_mfma_f32_16x16x32_bf16 v[120:123], v[148:151], v[164:167], v[120:123]
	v_mfma_f32_16x16x32_bf16 v[116:119], v[156:159], v[164:167], v[116:119]
	v_mfma_f32_16x16x32_bf16 v[104:107], v[148:151], v[172:175], v[104:107]
	v_mfma_f32_16x16x32_bf16 v[100:103], v[156:159], v[172:175], v[100:103]
	v_mfma_f32_16x16x32_bf16 v[88:91], v[148:151], v[180:183], v[88:91]
	v_mfma_f32_16x16x32_bf16 v[84:87], v[156:159], v[180:183], v[84:87]
	v_mfma_f32_16x16x32_bf16 v[72:75], v[148:151], v[188:191], v[72:75]
	v_mfma_f32_16x16x32_bf16 v[68:71], v[156:159], v[188:191], v[68:71]
	v_mfma_f32_16x16x32_bf16 v[120:123], v[152:155], v[168:171], v[120:123]
	v_mfma_f32_16x16x32_bf16 v[116:119], v[160:163], v[168:171], v[116:119]
	v_mfma_f32_16x16x32_bf16 v[104:107], v[152:155], v[176:179], v[104:107]
	v_mfma_f32_16x16x32_bf16 v[100:103], v[160:163], v[176:179], v[100:103]
	v_mfma_f32_16x16x32_bf16 v[88:91], v[152:155], v[184:187], v[88:91]
	v_mfma_f32_16x16x32_bf16 v[84:87], v[160:163], v[184:187], v[84:87]
	v_mfma_f32_16x16x32_bf16 v[72:75], v[152:155], v[192:195], v[72:75]
	v_mfma_f32_16x16x32_bf16 v[68:71], v[160:163], v[192:195], v[68:71]
	s_barrier
	s_setprio 0
	s_add_i32 s28, s53, s33
	v_lshl_add_u64 v[6:7], v[218:219], 0, s[2:3]
	s_mov_b32 m0, s28
	ds_read_b128 v[164:167], v224 offset:49152
	ds_read_b128 v[168:171], v224 offset:50176
	ds_read_b128 v[172:175], v224 offset:51200
	ds_read_b128 v[176:179], v224 offset:52224
	ds_read_b128 v[180:183], v224 offset:53248
	ds_read_b128 v[184:187], v224 offset:54272
	ds_read_b128 v[188:191], v224 offset:55296
	ds_read_b128 v[192:195], v224 offset:56320
	global_load_lds_dwordx4 v[6:7], off
	s_add_i32 m0, s28, 0x2000
	s_add_u32 s26, s26, 0x40080
	v_lshl_add_u64 v[6:7], v[220:221], 0, s[2:3]
	s_addc_u32 s27, s27, 0
	s_add_i32 s28, s54, s33
	global_load_lds_dwordx4 v[6:7], off
	v_lshl_add_u64 v[6:7], s[26:27], 0, v[200:201]
	s_mov_b32 m0, s28
	s_nop 0
	global_load_lds_dwordx4 v[6:7], off
	v_lshl_add_u64 v[6:7], s[26:27], 0, v[204:205]
	s_add_i32 m0, s28, 0x2000
	s_nop 0
	global_load_lds_dwordx4 v[6:7], off
	v_lshl_add_u64 v[6:7], v[226:227], 0, s[2:3]
	s_mov_b32 m0, s40
	s_nop 0
	global_load_lds_dwordx4 v[6:7], off
	v_lshl_add_u64 v[6:7], v[228:229], 0, s[2:3]
	s_mov_b32 m0, s41
	s_nop 0
	global_load_lds_dwordx4 v[6:7], off
	s_waitcnt vmcnt(8)
	s_waitcnt lgkmcnt(0)
	s_setprio 1
	s_barrier
	v_mfma_f32_16x16x32_bf16 v[64:67], v[132:135], v[164:167], v[64:67]
	v_mfma_f32_16x16x32_bf16 v[60:63], v[140:143], v[164:167], v[60:63]
	v_mfma_f32_16x16x32_bf16 v[48:51], v[132:135], v[172:175], v[48:51]
	v_mfma_f32_16x16x32_bf16 v[44:47], v[140:143], v[172:175], v[44:47]
	v_mfma_f32_16x16x32_bf16 v[32:35], v[132:135], v[180:183], v[32:35]
	v_mfma_f32_16x16x32_bf16 v[28:31], v[140:143], v[180:183], v[28:31]
	v_mfma_f32_16x16x32_bf16 v[16:19], v[132:135], v[188:191], v[16:19]
	v_mfma_f32_16x16x32_bf16 v[12:15], v[140:143], v[188:191], v[12:15]
	v_mfma_f32_16x16x32_bf16 v[64:67], v[136:139], v[168:171], v[64:67]
	v_mfma_f32_16x16x32_bf16 v[60:63], v[144:147], v[168:171], v[60:63]
	v_mfma_f32_16x16x32_bf16 v[48:51], v[136:139], v[176:179], v[48:51]
	v_mfma_f32_16x16x32_bf16 v[44:47], v[144:147], v[176:179], v[44:47]
	v_mfma_f32_16x16x32_bf16 v[32:35], v[136:139], v[184:187], v[32:35]
	v_mfma_f32_16x16x32_bf16 v[28:31], v[144:147], v[184:187], v[28:31]
	v_mfma_f32_16x16x32_bf16 v[16:19], v[136:139], v[192:195], v[16:19]
	v_mfma_f32_16x16x32_bf16 v[12:15], v[144:147], v[192:195], v[12:15]
	s_setprio 0
	s_setprio 1
	v_mfma_f32_16x16x32_bf16 v[56:59], v[148:151], v[164:167], v[56:59]
	v_mfma_f32_16x16x32_bf16 v[52:55], v[156:159], v[164:167], v[52:55]
	v_mfma_f32_16x16x32_bf16 v[40:43], v[148:151], v[172:175], v[40:43]
	v_mfma_f32_16x16x32_bf16 v[36:39], v[156:159], v[172:175], v[36:39]
	v_mfma_f32_16x16x32_bf16 v[24:27], v[148:151], v[180:183], v[24:27]
	v_mfma_f32_16x16x32_bf16 v[20:23], v[156:159], v[180:183], v[20:23]
	v_mfma_f32_16x16x32_bf16 v[6:9], v[148:151], v[188:191], v[8:11]
	v_mfma_f32_16x16x32_bf16 v[2:5], v[156:159], v[188:191], v[2:5]
	v_mfma_f32_16x16x32_bf16 v[56:59], v[152:155], v[168:171], v[56:59]
	v_mfma_f32_16x16x32_bf16 v[52:55], v[160:163], v[168:171], v[52:55]
	v_mfma_f32_16x16x32_bf16 v[40:43], v[152:155], v[176:179], v[40:43]
	v_mfma_f32_16x16x32_bf16 v[36:39], v[160:163], v[176:179], v[36:39]
	v_mfma_f32_16x16x32_bf16 v[24:27], v[152:155], v[184:187], v[24:27]
	v_mfma_f32_16x16x32_bf16 v[20:23], v[160:163], v[184:187], v[20:23]
	v_mfma_f32_16x16x32_bf16 v[8:11], v[152:155], v[192:195], v[6:9]
	v_mfma_f32_16x16x32_bf16 v[4:7], v[160:163], v[192:195], v[2:5]
	s_barrier
	s_setprio 0
	s_add_i32 s52, s52, 2
	s_add_u32 s24, s24, 0x100
	s_addc_u32 s25, s25, 0
	s_cmp_gt_u32 s52, 13
	s_cbranch_scc1 .LBB0_527

.LBB0_607:
	v_add_u32_e32 v147, s36, v145
	ds_read_b128 v[152:155], v147
	ds_read_b128 v[156:159], v147 offset:1024
	ds_read_b128 v[162:165], v147 offset:2048
	ds_read_b128 v[166:169], v147 offset:3072
	v_add_u32_e32 v147, s37, v145
	s_add_u32 s22, s2, s20
	ds_read_b128 v[172:175], v147
	ds_read_b128 v[176:179], v147 offset:1024
	ds_read_b128 v[180:183], v147 offset:2048
	ds_read_b128 v[184:187], v147 offset:3072
	s_addc_u32 s23, s3, s21
	s_add_u32 s22, s22, 0x100
	s_addc_u32 s23, s23, 0
	s_add_u32 s44, s39, s20
	s_addc_u32 s45, s40, s21
	s_cmpk_eq_i32 s20, 0x700
	s_cselect_b32 s25, s15, s23
	s_cselect_b32 s24, s41, s22
	s_cselect_b32 s23, s13, s45
	s_cselect_b32 s22, s42, s44
	v_lshl_add_u64 v[148:149], v[140:141], 0, s[20:21]
	s_add_i32 m0, s76, 0xc000
	ds_read_b128 v[188:191], v146
	ds_read_b128 v[192:195], v146 offset:1024
	ds_read_b128 v[196:199], v146 offset:2048
	ds_read_b128 v[200:203], v146 offset:3072
	ds_read_b128 v[204:207], v146 offset:4096
	ds_read_b128 v[208:211], v146 offset:5120
	ds_read_b128 v[212:215], v146 offset:6144
	ds_read_b128 v[216:219], v146 offset:7168
	global_load_lds_dwordx4 v[148:149], off
	v_lshl_add_u64 v[148:149], v[142:143], 0, s[20:21]
	s_add_i32 m0, s76, 0xe000
	s_nop 0
	global_load_lds_dwordx4 v[148:149], off
	s_waitcnt vmcnt(8)
	s_waitcnt lgkmcnt(0)
	s_setprio 1
	s_barrier
	v_mfma_f32_16x16x32_bf16 v[124:127], v[152:155], v[188:191], v[124:127]
	v_mfma_f32_16x16x32_bf16 v[120:123], v[162:165], v[188:191], v[120:123]
	v_mfma_f32_16x16x32_bf16 v[112:115], v[152:155], v[196:199], v[112:115]
	v_mfma_f32_16x16x32_bf16 v[104:107], v[162:165], v[196:199], v[104:107]
	v_mfma_f32_16x16x32_bf16 v[96:99], v[152:155], v[204:207], v[96:99]
	v_mfma_f32_16x16x32_bf16 v[88:91], v[162:165], v[204:207], v[88:91]
	v_mfma_f32_16x16x32_bf16 v[80:83], v[152:155], v[212:215], v[80:83]
	v_mfma_f32_16x16x32_bf16 v[72:75], v[162:165], v[212:215], v[72:75]
	v_mfma_f32_16x16x32_bf16 v[124:127], v[156:159], v[192:195], v[124:127]
	v_mfma_f32_16x16x32_bf16 v[120:123], v[166:169], v[192:195], v[120:123]
	v_mfma_f32_16x16x32_bf16 v[112:115], v[156:159], v[200:203], v[112:115]
	v_mfma_f32_16x16x32_bf16 v[104:107], v[166:169], v[200:203], v[104:107]
	v_mfma_f32_16x16x32_bf16 v[96:99], v[156:159], v[208:211], v[96:99]
	v_mfma_f32_16x16x32_bf16 v[88:91], v[166:169], v[208:211], v[88:91]
	v_mfma_f32_16x16x32_bf16 v[80:83], v[156:159], v[216:219], v[80:83]
	v_mfma_f32_16x16x32_bf16 v[72:75], v[166:169], v[216:219], v[72:75]
	s_setprio 0
	s_setprio 1
	v_mfma_f32_16x16x32_bf16 v[116:119], v[172:175], v[188:191], v[116:119]
	v_mfma_f32_16x16x32_bf16 v[108:111], v[180:183], v[188:191], v[108:111]
	v_mfma_f32_16x16x32_bf16 v[100:103], v[172:175], v[196:199], v[100:103]
	v_mfma_f32_16x16x32_bf16 v[92:95], v[180:183], v[196:199], v[92:95]
	v_mfma_f32_16x16x32_bf16 v[84:87], v[172:175], v[204:207], v[84:87]
	v_mfma_f32_16x16x32_bf16 v[76:79], v[180:183], v[204:207], v[76:79]
	v_mfma_f32_16x16x32_bf16 v[68:71], v[172:175], v[212:215], v[68:71]
	v_mfma_f32_16x16x32_bf16 v[64:67], v[180:183], v[212:215], v[64:67]
	v_mfma_f32_16x16x32_bf16 v[116:119], v[176:179], v[192:195], v[116:119]
	v_mfma_f32_16x16x32_bf16 v[108:111], v[184:187], v[192:195], v[108:111]
	v_mfma_f32_16x16x32_bf16 v[100:103], v[176:179], v[200:203], v[100:103]
	v_mfma_f32_16x16x32_bf16 v[92:95], v[184:187], v[200:203], v[92:95]
	v_mfma_f32_16x16x32_bf16 v[84:87], v[176:179], v[208:211], v[84:87]
	v_mfma_f32_16x16x32_bf16 v[76:79], v[184:187], v[208:211], v[76:79]
	v_mfma_f32_16x16x32_bf16 v[68:71], v[176:179], v[216:219], v[68:71]
	v_mfma_f32_16x16x32_bf16 v[64:67], v[184:187], v[216:219], v[64:67]
	s_barrier
	s_setprio 0
	s_add_i32 s44, s36, s33
	v_lshl_add_u64 v[148:149], s[22:23], 0, v[128:129]
	s_mov_b32 m0, s44
	ds_read_b128 v[188:191], v146 offset:16384
	ds_read_b128 v[192:195], v146 offset:17408
	ds_read_b128 v[196:199], v146 offset:18432
	ds_read_b128 v[200:203], v146 offset:19456
	ds_read_b128 v[204:207], v146 offset:20480
	ds_read_b128 v[208:211], v146 offset:21504
	ds_read_b128 v[212:215], v146 offset:22528
	ds_read_b128 v[216:219], v146 offset:23552
	global_load_lds_dwordx4 v[148:149], off
	s_add_i32 m0, s44, 0x2000
	s_add_u32 s44, s22, 0x40000
	v_lshl_add_u64 v[220:221], s[22:23], 0, v[130:131]
	s_addc_u32 s45, s23, 0
	s_add_i32 s46, s37, s33
	global_load_lds_dwordx4 v[220:221], off
	v_lshl_add_u64 v[222:223], s[44:45], 0, v[128:129]
	s_mov_b32 m0, s46
	v_lshl_add_u64 v[224:225], s[24:25], 0, v[130:131]
	global_load_lds_dwordx4 v[222:223], off
	v_lshl_add_u64 v[222:223], s[44:45], 0, v[130:131]
	s_add_i32 m0, s46, 0x2000
	s_nop 0
	global_load_lds_dwordx4 v[222:223], off
	v_lshl_add_u64 v[222:223], s[24:25], 0, v[128:129]
	s_mov_b32 m0, s76
	s_nop 0
	global_load_lds_dwordx4 v[222:223], off
	s_mov_b32 m0, s28
	s_nop 0
	global_load_lds_dwordx4 v[224:225], off
	s_waitcnt vmcnt(8)
	s_waitcnt lgkmcnt(0)
	s_setprio 1
	s_barrier
	v_mfma_f32_16x16x32_bf16 v[60:63], v[152:155], v[188:191], v[60:63]
	v_mfma_f32_16x16x32_bf16 v[56:59], v[162:165], v[188:191], v[56:59]
	v_mfma_f32_16x16x32_bf16 v[48:51], v[152:155], v[196:199], v[48:51]
	v_mfma_f32_16x16x32_bf16 v[40:43], v[162:165], v[196:199], v[40:43]
	v_mfma_f32_16x16x32_bf16 v[32:35], v[152:155], v[204:207], v[32:35]
	v_mfma_f32_16x16x32_bf16 v[24:27], v[162:165], v[204:207], v[24:27]
	v_mfma_f32_16x16x32_bf16 v[16:19], v[152:155], v[212:215], v[16:19]
	v_mfma_f32_16x16x32_bf16 v[8:11], v[162:165], v[212:215], v[8:11]
	v_mfma_f32_16x16x32_bf16 v[60:63], v[156:159], v[192:195], v[60:63]
	v_mfma_f32_16x16x32_bf16 v[56:59], v[166:169], v[192:195], v[56:59]
	v_mfma_f32_16x16x32_bf16 v[48:51], v[156:159], v[200:203], v[48:51]
	v_mfma_f32_16x16x32_bf16 v[40:43], v[166:169], v[200:203], v[40:43]
	v_mfma_f32_16x16x32_bf16 v[32:35], v[156:159], v[208:211], v[32:35]
	v_mfma_f32_16x16x32_bf16 v[24:27], v[166:169], v[208:211], v[24:27]
	v_mfma_f32_16x16x32_bf16 v[16:19], v[156:159], v[216:219], v[16:19]
	v_mfma_f32_16x16x32_bf16 v[8:11], v[166:169], v[216:219], v[8:11]
	s_setprio 0
	s_setprio 1
	v_mfma_f32_16x16x32_bf16 v[52:55], v[172:175], v[188:191], v[52:55]
	v_mfma_f32_16x16x32_bf16 v[44:47], v[180:183], v[188:191], v[44:47]
	v_mfma_f32_16x16x32_bf16 v[36:39], v[172:175], v[196:199], v[36:39]
	v_mfma_f32_16x16x32_bf16 v[28:31], v[180:183], v[196:199], v[28:31]
	v_mfma_f32_16x16x32_bf16 v[20:23], v[172:175], v[204:207], v[20:23]
	v_mfma_f32_16x16x32_bf16 v[12:15], v[180:183], v[204:207], v[12:15]
	v_mfma_f32_16x16x32_bf16 v[4:7], v[172:175], v[212:215], v[4:7]
	v_mfma_f32_16x16x32_bf16 v[0:3], v[180:183], v[212:215], v[0:3]
	v_mfma_f32_16x16x32_bf16 v[52:55], v[176:179], v[192:195], v[52:55]
	v_mfma_f32_16x16x32_bf16 v[44:47], v[184:187], v[192:195], v[44:47]
	v_mfma_f32_16x16x32_bf16 v[36:39], v[176:179], v[200:203], v[36:39]
	v_mfma_f32_16x16x32_bf16 v[28:31], v[184:187], v[200:203], v[28:31]
	v_mfma_f32_16x16x32_bf16 v[20:23], v[176:179], v[208:211], v[20:23]
	v_mfma_f32_16x16x32_bf16 v[12:15], v[184:187], v[208:211], v[12:15]
	v_mfma_f32_16x16x32_bf16 v[4:7], v[176:179], v[216:219], v[4:7]
	v_mfma_f32_16x16x32_bf16 v[0:3], v[184:187], v[216:219], v[0:3]
	s_barrier
	s_setprio 0
	s_add_i32 s44, 0, 0x18000
	v_add_u32_e32 v147, s44, v145
	s_add_i32 s45, 0, 0x1c000
	ds_read_b128 v[152:155], v147
	ds_read_b128 v[156:159], v147 offset:1024
	ds_read_b128 v[162:165], v147 offset:2048
	ds_read_b128 v[166:169], v147 offset:3072
	v_add_u32_e32 v147, s45, v145
	ds_read_b128 v[172:175], v147
	ds_read_b128 v[176:179], v147 offset:1024
	ds_read_b128 v[180:183], v147 offset:2048
	ds_read_b128 v[184:187], v147 offset:3072
	s_add_u32 s24, s24, 0x40000
	s_addc_u32 s25, s25, 0
	s_mov_b32 m0, s29
	v_lshl_add_u64 v[226:227], s[24:25], 0, v[128:129]
	ds_read_b128 v[188:191], v146 offset:32768
	ds_read_b128 v[192:195], v146 offset:33792
	ds_read_b128 v[196:199], v146 offset:34816
	ds_read_b128 v[200:203], v146 offset:35840
	ds_read_b128 v[204:207], v146 offset:36864
	ds_read_b128 v[208:211], v146 offset:37888
	ds_read_b128 v[212:215], v146 offset:38912
	ds_read_b128 v[216:219], v146 offset:39936
	global_load_lds_dwordx4 v[226:227], off
	v_lshl_add_u64 v[226:227], s[24:25], 0, v[130:131]
	s_mov_b32 m0, s30
	s_nop 0
	global_load_lds_dwordx4 v[226:227], off
	s_waitcnt vmcnt(8)
	s_waitcnt lgkmcnt(0)
	s_setprio 1
	s_barrier
	v_mfma_f32_16x16x32_bf16 v[124:127], v[152:155], v[188:191], v[124:127]
	v_mfma_f32_16x16x32_bf16 v[120:123], v[162:165], v[188:191], v[120:123]
	v_mfma_f32_16x16x32_bf16 v[112:115], v[152:155], v[196:199], v[112:115]
	v_mfma_f32_16x16x32_bf16 v[104:107], v[162:165], v[196:199], v[104:107]
	v_mfma_f32_16x16x32_bf16 v[96:99], v[152:155], v[204:207], v[96:99]
	v_mfma_f32_16x16x32_bf16 v[88:91], v[162:165], v[204:207], v[88:91]
	v_mfma_f32_16x16x32_bf16 v[80:83], v[152:155], v[212:215], v[80:83]
	v_mfma_f32_16x16x32_bf16 v[72:75], v[162:165], v[212:215], v[72:75]
	v_mfma_f32_16x16x32_bf16 v[124:127], v[156:159], v[192:195], v[124:127]
	v_mfma_f32_16x16x32_bf16 v[120:123], v[166:169], v[192:195], v[120:123]
	v_mfma_f32_16x16x32_bf16 v[112:115], v[156:159], v[200:203], v[112:115]
	v_mfma_f32_16x16x32_bf16 v[104:107], v[166:169], v[200:203], v[104:107]
	v_mfma_f32_16x16x32_bf16 v[96:99], v[156:159], v[208:211], v[96:99]
	v_mfma_f32_16x16x32_bf16 v[88:91], v[166:169], v[208:211], v[88:91]
	v_mfma_f32_16x16x32_bf16 v[80:83], v[156:159], v[216:219], v[80:83]
	v_mfma_f32_16x16x32_bf16 v[72:75], v[166:169], v[216:219], v[72:75]
	s_setprio 0
	s_setprio 1
	v_mfma_f32_16x16x32_bf16 v[116:119], v[172:175], v[188:191], v[116:119]
	v_mfma_f32_16x16x32_bf16 v[108:111], v[180:183], v[188:191], v[108:111]
	v_mfma_f32_16x16x32_bf16 v[100:103], v[172:175], v[196:199], v[100:103]
	v_mfma_f32_16x16x32_bf16 v[92:95], v[180:183], v[196:199], v[92:95]
	v_mfma_f32_16x16x32_bf16 v[84:87], v[172:175], v[204:207], v[84:87]
	v_mfma_f32_16x16x32_bf16 v[76:79], v[180:183], v[204:207], v[76:79]
	v_mfma_f32_16x16x32_bf16 v[68:71], v[172:175], v[212:215], v[68:71]
	v_mfma_f32_16x16x32_bf16 v[64:67], v[180:183], v[212:215], v[64:67]
	v_mfma_f32_16x16x32_bf16 v[116:119], v[176:179], v[192:195], v[116:119]
	v_mfma_f32_16x16x32_bf16 v[108:111], v[184:187], v[192:195], v[108:111]
	v_mfma_f32_16x16x32_bf16 v[100:103], v[176:179], v[200:203], v[100:103]
	v_mfma_f32_16x16x32_bf16 v[92:95], v[184:187], v[200:203], v[92:95]
	v_mfma_f32_16x16x32_bf16 v[84:87], v[176:179], v[208:211], v[84:87]
	v_mfma_f32_16x16x32_bf16 v[76:79], v[184:187], v[208:211], v[76:79]
	v_mfma_f32_16x16x32_bf16 v[68:71], v[176:179], v[216:219], v[68:71]
	v_mfma_f32_16x16x32_bf16 v[64:67], v[184:187], v[216:219], v[64:67]
	s_barrier
	s_setprio 0
	s_add_i32 s24, s44, s33
	v_lshl_add_u64 v[148:149], v[148:149], 0, s[10:11]
	s_mov_b32 m0, s24
	ds_read_b128 v[188:191], v146 offset:49152
	ds_read_b128 v[192:195], v146 offset:50176
	ds_read_b128 v[196:199], v146 offset:51200
	ds_read_b128 v[200:203], v146 offset:52224
	ds_read_b128 v[204:207], v146 offset:53248
	ds_read_b128 v[208:211], v146 offset:54272
	ds_read_b128 v[212:215], v146 offset:55296
	ds_read_b128 v[216:219], v146 offset:56320
	global_load_lds_dwordx4 v[148:149], off
	s_add_i32 m0, s24, 0x2000
	s_add_u32 s22, s22, 0x40080
	v_lshl_add_u64 v[148:149], v[220:221], 0, s[10:11]
	s_addc_u32 s23, s23, 0
	s_add_i32 s24, s45, s33
	global_load_lds_dwordx4 v[148:149], off
	v_lshl_add_u64 v[148:149], s[22:23], 0, v[128:129]
	s_mov_b32 m0, s24
	s_nop 0
	global_load_lds_dwordx4 v[148:149], off
	v_lshl_add_u64 v[148:149], s[22:23], 0, v[130:131]
	s_add_i32 m0, s24, 0x2000
	s_nop 0
	global_load_lds_dwordx4 v[148:149], off
	v_lshl_add_u64 v[148:149], v[222:223], 0, s[10:11]
	s_mov_b32 m0, s31
	s_nop 0
	global_load_lds_dwordx4 v[148:149], off
	v_lshl_add_u64 v[148:149], v[224:225], 0, s[10:11]
	s_mov_b32 m0, s34
	s_nop 0
	global_load_lds_dwordx4 v[148:149], off
	s_waitcnt vmcnt(8)
	s_waitcnt lgkmcnt(0)
	s_setprio 1
	s_barrier
	v_mfma_f32_16x16x32_bf16 v[60:63], v[152:155], v[188:191], v[60:63]
	v_mfma_f32_16x16x32_bf16 v[56:59], v[162:165], v[188:191], v[56:59]
	v_mfma_f32_16x16x32_bf16 v[48:51], v[152:155], v[196:199], v[48:51]
	v_mfma_f32_16x16x32_bf16 v[40:43], v[162:165], v[196:199], v[40:43]
	v_mfma_f32_16x16x32_bf16 v[32:35], v[152:155], v[204:207], v[32:35]
	v_mfma_f32_16x16x32_bf16 v[24:27], v[162:165], v[204:207], v[24:27]
	v_mfma_f32_16x16x32_bf16 v[16:19], v[152:155], v[212:215], v[16:19]
	v_mfma_f32_16x16x32_bf16 v[8:11], v[162:165], v[212:215], v[8:11]
	v_mfma_f32_16x16x32_bf16 v[60:63], v[156:159], v[192:195], v[60:63]
	v_mfma_f32_16x16x32_bf16 v[56:59], v[166:169], v[192:195], v[56:59]
	v_mfma_f32_16x16x32_bf16 v[48:51], v[156:159], v[200:203], v[48:51]
	v_mfma_f32_16x16x32_bf16 v[40:43], v[166:169], v[200:203], v[40:43]
	v_mfma_f32_16x16x32_bf16 v[32:35], v[156:159], v[208:211], v[32:35]
	v_mfma_f32_16x16x32_bf16 v[24:27], v[166:169], v[208:211], v[24:27]
	v_mfma_f32_16x16x32_bf16 v[16:19], v[156:159], v[216:219], v[16:19]
	v_mfma_f32_16x16x32_bf16 v[8:11], v[166:169], v[216:219], v[8:11]
	s_setprio 0
	s_setprio 1
	v_mfma_f32_16x16x32_bf16 v[52:55], v[172:175], v[188:191], v[52:55]
	v_mfma_f32_16x16x32_bf16 v[44:47], v[180:183], v[188:191], v[44:47]
	v_mfma_f32_16x16x32_bf16 v[36:39], v[172:175], v[196:199], v[36:39]
	v_mfma_f32_16x16x32_bf16 v[28:31], v[180:183], v[196:199], v[28:31]
	v_mfma_f32_16x16x32_bf16 v[20:23], v[172:175], v[204:207], v[20:23]
	v_mfma_f32_16x16x32_bf16 v[12:15], v[180:183], v[204:207], v[12:15]
	v_mfma_f32_16x16x32_bf16 v[4:7], v[172:175], v[212:215], v[4:7]
	v_mfma_f32_16x16x32_bf16 v[0:3], v[180:183], v[212:215], v[0:3]
	v_mfma_f32_16x16x32_bf16 v[52:55], v[176:179], v[192:195], v[52:55]
	v_mfma_f32_16x16x32_bf16 v[44:47], v[184:187], v[192:195], v[44:47]
	v_mfma_f32_16x16x32_bf16 v[36:39], v[176:179], v[200:203], v[36:39]
	v_mfma_f32_16x16x32_bf16 v[28:31], v[184:187], v[200:203], v[28:31]
	v_mfma_f32_16x16x32_bf16 v[20:23], v[176:179], v[208:211], v[20:23]
	v_mfma_f32_16x16x32_bf16 v[12:15], v[184:187], v[208:211], v[12:15]
	v_mfma_f32_16x16x32_bf16 v[4:7], v[176:179], v[216:219], v[4:7]
	v_mfma_f32_16x16x32_bf16 v[0:3], v[184:187], v[216:219], v[0:3]
	s_barrier
	s_setprio 0
	s_add_i32 s43, s43, 2
	s_add_u32 s20, s20, 0x100
	s_addc_u32 s21, s21, 0
	s_cmp_gt_u32 s43, 13
	s_cbranch_scc0 .LBB0_607
	s_add_u32 s20, s39, 0xffffff00
	s_addc_u32 s21, s40, -1
	s_andn2_b64 vcc, exec, s[4:5]
	s_cbranch_vccnz .LBB0_610
	v_mov_b32_e32 v0, 0
	s_mov_b32 s8, s12
	s_mov_b32 s6, s14
	s_mov_b64 s[2:3], s[18:19]
	s_mov_b32 s35, s38
	v_mov_b32_e32 v1, v0
	v_mov_b32_e32 v2, v0
	v_mov_b32_e32 v3, v0
	v_mov_b32_e32 v4, v0
	v_mov_b32_e32 v5, v0
	v_mov_b32_e32 v6, v0
	v_mov_b32_e32 v7, v0
	v_mov_b32_e32 v12, v0
	v_mov_b32_e32 v13, v0
	v_mov_b32_e32 v14, v0
	v_mov_b32_e32 v15, v0
	v_mov_b32_e32 v20, v0
	v_mov_b32_e32 v21, v0
	v_mov_b32_e32 v22, v0
	v_mov_b32_e32 v23, v0
	v_mov_b32_e32 v28, v0
	v_mov_b32_e32 v29, v0
	v_mov_b32_e32 v30, v0
	v_mov_b32_e32 v31, v0
	v_mov_b32_e32 v36, v0
	v_mov_b32_e32 v37, v0
	v_mov_b32_e32 v38, v0
	v_mov_b32_e32 v39, v0
	v_mov_b32_e32 v44, v0
	v_mov_b32_e32 v45, v0
	v_mov_b32_e32 v46, v0
	v_mov_b32_e32 v47, v0
	v_mov_b32_e32 v52, v0
	v_mov_b32_e32 v53, v0
	v_mov_b32_e32 v54, v0
	v_mov_b32_e32 v55, v0
	v_mov_b32_e32 v8, v0
	v_mov_b32_e32 v9, v0
	v_mov_b32_e32 v10, v0
	v_mov_b32_e32 v11, v0
	v_mov_b32_e32 v16, v0
	v_mov_b32_e32 v17, v0
	v_mov_b32_e32 v18, v0
	v_mov_b32_e32 v19, v0
	v_mov_b32_e32 v24, v0
	v_mov_b32_e32 v25, v0
	v_mov_b32_e32 v26, v0
	v_mov_b32_e32 v27, v0
	v_mov_b32_e32 v32, v0
	v_mov_b32_e32 v33, v0
	v_mov_b32_e32 v34, v0
	v_mov_b32_e32 v35, v0
	v_mov_b32_e32 v40, v0
	v_mov_b32_e32 v41, v0
	v_mov_b32_e32 v42, v0
	v_mov_b32_e32 v43, v0
	v_mov_b32_e32 v48, v0
	v_mov_b32_e32 v49, v0
	v_mov_b32_e32 v50, v0
	v_mov_b32_e32 v51, v0
	v_mov_b32_e32 v56, v0
	v_mov_b32_e32 v57, v0
	v_mov_b32_e32 v58, v0
	v_mov_b32_e32 v59, v0
	v_mov_b32_e32 v60, v0
	v_mov_b32_e32 v61, v0
	v_mov_b32_e32 v62, v0
	v_mov_b32_e32 v63, v0
	v_mov_b32_e32 v64, v0
	v_mov_b32_e32 v65, v0
	v_mov_b32_e32 v66, v0
	v_mov_b32_e32 v67, v0
	v_mov_b32_e32 v68, v0
	v_mov_b32_e32 v69, v0
	v_mov_b32_e32 v70, v0
	v_mov_b32_e32 v71, v0
	v_mov_b32_e32 v76, v0
	v_mov_b32_e32 v77, v0
	v_mov_b32_e32 v78, v0
	v_mov_b32_e32 v79, v0
	v_mov_b32_e32 v84, v0
	v_mov_b32_e32 v85, v0
	v_mov_b32_e32 v86, v0
	v_mov_b32_e32 v87, v0
	v_mov_b32_e32 v92, v0
	v_mov_b32_e32 v93, v0
	v_mov_b32_e32 v94, v0
	v_mov_b32_e32 v95, v0
	v_mov_b32_e32 v100, v0
	v_mov_b32_e32 v101, v0
	v_mov_b32_e32 v102, v0
	v_mov_b32_e32 v103, v0
	v_mov_b32_e32 v108, v0
	v_mov_b32_e32 v109, v0
	v_mov_b32_e32 v110, v0
	v_mov_b32_e32 v111, v0
	v_mov_b32_e32 v116, v0
	v_mov_b32_e32 v117, v0
	v_mov_b32_e32 v118, v0
	v_mov_b32_e32 v119, v0
	v_mov_b32_e32 v72, v0
	v_mov_b32_e32 v73, v0
	v_mov_b32_e32 v74, v0
	v_mov_b32_e32 v75, v0
	v_mov_b32_e32 v80, v0
	v_mov_b32_e32 v81, v0
	v_mov_b32_e32 v82, v0
	v_mov_b32_e32 v83, v0
	v_mov_b32_e32 v88, v0
	v_mov_b32_e32 v89, v0
	v_mov_b32_e32 v90, v0
	v_mov_b32_e32 v91, v0
	v_mov_b32_e32 v96, v0
	v_mov_b32_e32 v97, v0
	v_mov_b32_e32 v98, v0
	v_mov_b32_e32 v99, v0
	v_mov_b32_e32 v104, v0
	v_mov_b32_e32 v105, v0
	v_mov_b32_e32 v106, v0
	v_mov_b32_e32 v107, v0
	v_mov_b32_e32 v112, v0
	v_mov_b32_e32 v113, v0
	v_mov_b32_e32 v114, v0
	v_mov_b32_e32 v115, v0
	v_mov_b32_e32 v120, v0
	v_mov_b32_e32 v121, v0
	v_mov_b32_e32 v122, v0
	v_mov_b32_e32 v123, v0
	v_mov_b32_e32 v124, v0
	v_mov_b32_e32 v125, v0
	v_mov_b32_e32 v126, v0
	v_mov_b32_e32 v127, v0
	s_andn2_b64 vcc, exec, s[0:1]
	s_cbranch_vccnz .LBB0_611
	s_branch .LBB0_612
